# in-proj 256x128 tiles remapped so each XCD (bid mod 8) owns whole m-tiles (A rows shared in its L2)
# baseline (speedup 1.0000x reference)
; __device__ __forceinline__ int launder(int x) { asm volatile("" : "+v"(x)); return x; }
; __device__ __forceinline__ void gemm_tile256(const Params& p, int l, int mt_, int nt_, unsigned char* smem) {
;   const bf16_t* A = p.hbuf;
;   const bf16_t* Bt = p.WtIn + (size_t)l * 3712 * 1024;
;   const int m0 = mt_ * 256, n0 = nt_ * 128;
;   const int tid = launder(threadIdx.x), lane = tid & 63, w = tid >> 6, fr = lane & 15, fq = lane >> 4;
;   f32x4 acc[4][8];
; #pragma unroll
;   for (int i = 0; i < 4; ++i)
; #pragma unroll
;     for (int j = 0; j < 8; ++j) acc[i][j] = (f32x4){0.f, 0.f, 0.f, 0.f};
;   unsigned char* lds = smem;
;   int sR[4], sC[4];
; #pragma unroll
;   for (int i = 0; i < 4; ++i) {
;     const int bo = tid * 16 + i * 4096;
;     const int st = bo >> 10, sb = bo & 1023, swz = sb ^ (((sb >> 9) & 1) << 5);
;     sR[i] = st * 16 + (swz >> 6);
;     sC[i] = (swz & 63) >> 1;
;   }
;   const bf16_t* Ag0 = A + (size_t)(m0 + sR[0]) * 1024 + sC[0];
;   const bf16_t* Ag1 = A + (size_t)(m0 + sR[1]) * 1024 + sC[1];
;   const bf16_t* Ag2 = A + (size_t)(m0 + sR[2]) * 1024 + sC[2];
;   const bf16_t* Ag3 = A + (size_t)(m0 + sR[3]) * 1024 + sC[3];
;   const bf16_t* Bg0 = Bt + (size_t)(n0 + sR[0]) * 1024 + sC[0];
;   const bf16_t* Bg1 = Bt + (size_t)(n0 + sR[1]) * 1024 + sC[1];
;     ...
;   const int lo = (fr * 64 + fq * 16) ^ ((fr >> 3) << 5);
;   GQ_STAGE(0, 0);
; __device__ __forceinline__ void phase_inproj(const Params& p, int l, unsigned char* smem) {
;   if ((gridDim.x & 7) == 0) {
;     const int x = blockIdx.x & 7, slot = blockIdx.x >> 3, nslot = gridDim.x >> 3;
;     (void)x; (void)slot; (void)nslot;
;     for (int t = blockIdx.x; t < 64 * 24; t += gridDim.x) { const int ne = t % 24; gemm_tile256(p, l, t / 24, (ne < 16) ? ne : ne + 5, smem); }
.LBB0_947:
	s_lshr_b32 s44, s28, 3
	s_mul_hi_i32 s42, s44, 0x2aaaaaab
	s_lshr_b32 s43, s42, 31
	s_ashr_i32 s42, s42, 2
	s_add_i32 s42, s42, s43
	s_mul_i32 s43, s42, 24
	v_mov_b32_e32 v186, v189
	s_sub_i32 s43, s44, s43
	s_lshl_b32 s42, s42, 3
	s_and_b32 s44, s28, 7
	s_or_b32 s42, s42, s44
	s_add_i32 s44, s43, 5
	v_lshlrev_b32_e32 v14, 4, v186
	v_lshrrev_b32_e32 v216, 2, v186
	v_ashrrev_i32_e32 v1, 2, v186
	v_and_b32_e32 v18, -16, v1
	v_bfi_b32 v10, 15, v216, v1
	v_add_u32_e32 v1, 0x1000, v14
	s_cmp_lt_i32 s43, 16
	v_ashrrev_i32_e32 v1, 6, v1
	s_cselect_b32 s46, s43, s44
	s_lshl_b32 s44, s42, 8
	v_and_b32_e32 v19, -16, v1
	v_bfi_b32 v12, -16, v1, v216
	v_add_u32_e32 v1, 0x2000, v14
	v_ashrrev_i32_e32 v1, 6, v1
	v_add_u32_e32 v2, s44, v10
	v_and_b32_e32 v20, -16, v1
	v_add_u32_e32 v1, 0x3000, v14
	v_ashrrev_i32_e32 v3, 31, v2
	v_readlane_b32 s0, v251, 48
	v_and_b32_e32 v15, 32, v186
	v_bfe_u32 v16, v186, 2, 4
	v_ashrrev_i32_e32 v1, 6, v1
	v_lshlrev_b64 v[2:3], 11, v[2:3]
	v_readlane_b32 s6, v251, 54
	v_readlane_b32 s7, v251, 55
	v_add_u32_e32 v141, 0, v14
	v_bitop3_b32 v0, v14, v15, 48 bitop3:0x6c
	v_and_b32_e32 v21, -16, v1
	v_lshl_add_u64 v[2:3], s[6:7], 0, v[2:3]
	v_mov_b32_e32 v1, v164
	v_add_u32_e32 v4, s44, v12
	v_or_b32_e32 v8, s44, v16
	v_readfirstlane_b32 s42, v141
	v_lshl_add_u64 v[2:3], v[2:3], 0, v[0:1]
	v_ashrrev_i32_e32 v5, 31, v4
	v_add_u32_e32 v6, v8, v20
	s_mov_b32 m0, s42
	s_lshl_b32 s92, s46, 7
	v_lshlrev_b64 v[4:5], 11, v[4:5]
	v_ashrrev_i32_e32 v7, 31, v6
	v_add_u32_e32 v8, v8, v21
	global_load_lds_dwordx4 v[2:3], off
	v_add_u32_e32 v2, 0x1000, v141
	v_lshl_add_u64 v[4:5], s[6:7], 0, v[4:5]
	v_lshlrev_b64 v[6:7], 11, v[6:7]
	v_ashrrev_i32_e32 v9, 31, v8
	v_add_u32_e32 v10, s92, v10
	v_readfirstlane_b32 s42, v2
	v_add_u32_e32 v2, 0x2000, v141
	v_readlane_b32 s1, v251, 49
	v_lshl_add_u64 v[4:5], v[4:5], 0, v[0:1]
	v_lshl_add_u64 v[6:7], s[6:7], 0, v[6:7]
	v_lshlrev_b64 v[8:9], 11, v[8:9]
	v_ashrrev_i32_e32 v11, 31, v10
	v_add_u32_e32 v12, s92, v12
	s_mov_b32 m0, s42
	v_readfirstlane_b32 s42, v2
	v_add_u32_e32 v2, 0x3000, v141
	v_lshl_add_u64 v[6:7], v[6:7], 0, v[0:1]
	v_lshl_add_u64 v[8:9], s[6:7], 0, v[8:9]
	v_lshlrev_b64 v[10:11], 11, v[10:11]
	s_mov_b64 s[0:1], s[82:83]
	v_ashrrev_i32_e32 v13, 31, v12
	global_load_lds_dwordx4 v[4:5], off
	s_mov_b32 m0, s42
	v_readfirstlane_b32 s42, v2
	v_add_u32_e32 v2, 0x4000, v141
	v_lshl_add_u64 v[8:9], v[8:9], 0, v[0:1]
	v_lshl_add_u64 v[10:11], s[0:1], 0, v[10:11]
	v_lshlrev_b64 v[12:13], 11, v[12:13]
	global_load_lds_dwordx4 v[6:7], off
	s_mov_b32 m0, s42
	v_readfirstlane_b32 s42, v2
	v_add_u32_e32 v2, 0x5000, v141
	v_lshl_add_u64 v[10:11], v[10:11], 0, v[0:1]
	v_lshl_add_u64 v[12:13], s[0:1], 0, v[12:13]
	global_load_lds_dwordx4 v[8:9], off
	s_mov_b32 m0, s42
	v_readfirstlane_b32 s42, v2
	v_lshl_add_u64 v[0:1], v[12:13], 0, v[0:1]
	global_load_lds_dwordx4 v[10:11], off
	s_mov_b32 m0, s42
	v_and_b32_e32 v17, 48, v14
	global_load_lds_dwordx4 v[0:1], off
	v_add_u32_e32 v0, s44, v18
	v_or_b32_e32 v0, v0, v16
	v_ashrrev_i32_e32 v1, 31, v0
	v_lshlrev_b64 v[0:1], 11, v[0:1]
	v_readlane_b32 s0, v254, 56
	v_bitop3_b32 v0, v0, v17, v15 bitop3:0xf6
	v_readlane_b32 s1, v254, 57
	v_and_b32_e32 v165, 15, v186
	v_lshlrev_b32_e32 v22, 2, v186
	v_lshl_add_u64 v[92:93], s[0:1], 0, v[0:1]
	v_add_u32_e32 v0, s44, v19
	v_or_b32_e32 v0, v0, v16
	v_ashrrev_i32_e32 v1, 31, v0
	v_lshlrev_b64 v[0:1], 11, v[0:1]
	v_bitop3_b32 v0, v0, v17, v15 bitop3:0xf6
	v_lshl_add_u64 v[94:95], s[0:1], 0, v[0:1]
	v_add_u32_e32 v0, s44, v20
	v_or_b32_e32 v0, v0, v16
	v_ashrrev_i32_e32 v1, 31, v0
	v_lshlrev_b64 v[0:1], 11, v[0:1]
	v_bitop3_b32 v0, v0, v17, v15 bitop3:0xf6
	v_lshl_add_u64 v[132:133], s[0:1], 0, v[0:1]
	v_add_u32_e32 v0, s44, v21
	v_or_b32_e32 v0, v0, v16
	v_ashrrev_i32_e32 v1, 31, v0
	v_lshlrev_b64 v[0:1], 11, v[0:1]
	v_bitop3_b32 v0, v0, v17, v15 bitop3:0xf6
	v_lshl_add_u64 v[134:135], s[0:1], 0, v[0:1]
	v_add_u32_e32 v0, s92, v18
	v_or_b32_e32 v0, v0, v16
	v_ashrrev_i32_e32 v1, 31, v0
	v_lshlrev_b64 v[0:1], 11, v[0:1]
	v_bitop3_b32 v0, v0, v17, v15 bitop3:0xf6
	v_lshl_add_u64 v[136:137], s[94:95], 0, v[0:1]
	v_add_u32_e32 v0, s92, v19
	v_or_b32_e32 v0, v0, v16
	v_ashrrev_i32_e32 v1, 31, v0
	v_lshlrev_b64 v[0:1], 11, v[0:1]
	s_nop 0
; __device__ __forceinline__ int launder(int x) { asm volatile("" : "+v"(x)); return x; }
; __device__ __forceinline__ void gemm_tile256(const Params& p, int l, int mt_, int nt_, unsigned char* smem) {
;     ...
;   const int tid = launder(threadIdx.x), lane = tid & 63, w = tid >> 6, fr = lane & 15, fq = lane >> 4;
;   f32x4 acc[4][8];
; #pragma unroll
;   for (int i = 0; i < 4; ++i)
; #pragma unroll
;     for (int j = 0; j < 8; ++j) acc[i][j] = (f32x4){0.f, 0.f, 0.f, 0.f};
;   unsigned char* lds = smem;
;   int sR[4], sC[4];
; #pragma unroll
;   for (int i = 0; i < 4; ++i) {
;     const int bo = tid * 16 + i * 4096;
;     const int st = bo >> 10, sb = bo & 1023, swz = sb ^ (((sb >> 9) & 1) << 5);
;     sR[i] = st * 16 + (swz >> 6);
;     sC[i] = (swz & 63) >> 1;
;   }
;   const bf16_t* Ag0 = A + (size_t)(m0 + sR[0]) * 1024 + sC[0];
;   const bf16_t* Ag1 = A + (size_t)(m0 + sR[1]) * 1024 + sC[1];
;   const bf16_t* Ag2 = A + (size_t)(m0 + sR[2]) * 1024 + sC[2];
;   const bf16_t* Ag3 = A + (size_t)(m0 + sR[3]) * 1024 + sC[3];
;   const bf16_t* Bg0 = Bt + (size_t)(n0 + sR[0]) * 1024 + sC[0];
;   const bf16_t* Bg1 = Bt + (size_t)(n0 + sR[1]) * 1024 + sC[1];
;     ...
;   const int lo = (fr * 64 + fq * 16) ^ ((fr >> 3) << 5);
;   GQ_STAGE(0, 0);
;   asm volatile("s_waitcnt vmcnt(0)" ::: "memory");
;   __builtin_amdgcn_s_barrier();
;   for (int kt = 0; kt < 32; ++kt) {
;     const int q = kt & 1;
;     if (kt + 1 < 32) GQ_STAGE(q ^ 1, kt + 1);
	v_bitop3_b32 v0, v0, v17, v15 bitop3:0xf6
	v_lshlrev_b32_e32 v12, 6, v165
	v_and_b32_e32 v13, 48, v186
	v_and_b32_e32 v22, 32, v22
	v_lshl_add_u64 v[138:139], s[94:95], 0, v[0:1]
	v_mov_b32_e32 v0, 0
	v_ashrrev_i32_e32 v217, 6, v186
	v_bitop3_b32 v140, v12, v22, v13 bitop3:0x36
	s_mov_b32 s45, 0
	s_mov_b64 s[42:43], 0
	v_mov_b32_e32 v1, v0
	v_mov_b32_e32 v2, v0
	v_mov_b32_e32 v3, v0
	v_mov_b32_e32 v4, v0
	v_mov_b32_e32 v5, v0
	v_mov_b32_e32 v6, v0
	v_mov_b32_e32 v7, v0
	v_mov_b32_e32 v8, v0
	v_mov_b32_e32 v9, v0
	v_mov_b32_e32 v10, v0
	v_mov_b32_e32 v11, v0
	v_mov_b32_e32 v12, v0
	v_mov_b32_e32 v13, v0
	v_mov_b32_e32 v14, v0
	v_mov_b32_e32 v15, v0
	v_mov_b32_e32 v20, v0
	v_mov_b32_e32 v21, v0
	v_mov_b32_e32 v22, v0
	v_mov_b32_e32 v23, v0
	s_nop 0
	v_mov_b32_e32 v28, v0
	v_mov_b32_e32 v29, v0
	v_mov_b32_e32 v30, v0
	v_mov_b32_e32 v31, v0
	v_mov_b32_e32 v36, v0
	v_mov_b32_e32 v37, v0
	v_mov_b32_e32 v38, v0
	v_mov_b32_e32 v39, v0
	v_mov_b32_e32 v44, v0
	v_mov_b32_e32 v45, v0
	v_mov_b32_e32 v46, v0
	v_mov_b32_e32 v47, v0
	v_mov_b32_e32 v16, v0
	v_mov_b32_e32 v17, v0
	v_mov_b32_e32 v18, v0
	v_mov_b32_e32 v19, v0
	v_mov_b32_e32 v24, v0
	v_mov_b32_e32 v25, v0
	v_mov_b32_e32 v26, v0
	v_mov_b32_e32 v27, v0
	v_mov_b32_e32 v32, v0
	v_mov_b32_e32 v33, v0
	v_mov_b32_e32 v34, v0
	v_mov_b32_e32 v35, v0
	v_mov_b32_e32 v40, v0
	v_mov_b32_e32 v41, v0
	v_mov_b32_e32 v42, v0
	v_mov_b32_e32 v43, v0
	v_mov_b32_e32 v56, v0
	v_mov_b32_e32 v57, v0
	v_mov_b32_e32 v58, v0
	v_mov_b32_e32 v59, v0
	v_mov_b32_e32 v60, v0
	v_mov_b32_e32 v61, v0
	v_mov_b32_e32 v62, v0
	v_mov_b32_e32 v63, v0
	v_mov_b32_e32 v64, v0
	v_mov_b32_e32 v65, v0
	v_mov_b32_e32 v66, v0
	v_mov_b32_e32 v67, v0
	v_mov_b32_e32 v68, v0
	v_mov_b32_e32 v69, v0
	v_mov_b32_e32 v70, v0
	v_mov_b32_e32 v71, v0
	v_mov_b32_e32 v52, v0
	v_mov_b32_e32 v53, v0
	v_mov_b32_e32 v54, v0
	v_mov_b32_e32 v55, v0
	v_mov_b32_e32 v48, v0
	v_mov_b32_e32 v49, v0
	v_mov_b32_e32 v50, v0
	v_mov_b32_e32 v51, v0
	v_mov_b32_e32 v96, v0
	v_mov_b32_e32 v97, v0
	v_mov_b32_e32 v98, v0
	v_mov_b32_e32 v99, v0
	v_mov_b32_e32 v100, v0
	v_mov_b32_e32 v101, v0
	v_mov_b32_e32 v102, v0
	v_mov_b32_e32 v103, v0
	v_mov_b32_e32 v72, v0
	v_mov_b32_e32 v73, v0
	v_mov_b32_e32 v74, v0
	v_mov_b32_e32 v75, v0
	v_mov_b32_e32 v80, v0
	v_mov_b32_e32 v81, v0
	v_mov_b32_e32 v82, v0
	v_mov_b32_e32 v83, v0
	v_mov_b32_e32 v84, v0
	v_mov_b32_e32 v85, v0
	v_mov_b32_e32 v86, v0
	v_mov_b32_e32 v87, v0
	v_mov_b32_e32 v88, v0
	v_mov_b32_e32 v89, v0
	v_mov_b32_e32 v90, v0
	v_mov_b32_e32 v91, v0
	v_mov_b32_e32 v76, v0
	v_mov_b32_e32 v77, v0
	v_mov_b32_e32 v78, v0
	v_mov_b32_e32 v79, v0
	v_mov_b32_e32 v120, v0
	v_mov_b32_e32 v121, v0
	v_mov_b32_e32 v122, v0
	v_mov_b32_e32 v123, v0
	v_mov_b32_e32 v124, v0
	v_mov_b32_e32 v125, v0
	v_mov_b32_e32 v126, v0
	v_mov_b32_e32 v127, v0
	v_mov_b32_e32 v128, v0
	v_mov_b32_e32 v129, v0
	v_mov_b32_e32 v130, v0
	v_mov_b32_e32 v131, v0
	v_mov_b32_e32 v104, v0
	v_mov_b32_e32 v105, v0
	v_mov_b32_e32 v106, v0
	v_mov_b32_e32 v107, v0
	v_mov_b32_e32 v108, v0
	v_mov_b32_e32 v109, v0
	v_mov_b32_e32 v110, v0
	v_mov_b32_e32 v111, v0
	v_mov_b32_e32 v116, v0
	v_mov_b32_e32 v117, v0
	v_mov_b32_e32 v118, v0
	v_mov_b32_e32 v119, v0
	v_mov_b32_e32 v112, v0
	v_mov_b32_e32 v113, v0
	v_mov_b32_e32 v114, v0
	v_mov_b32_e32 v115, v0
	v_lshlrev_b32_e32 v142, 12, v217
	v_readlane_b32 s2, v251, 50
	v_readlane_b32 s3, v251, 51
	v_readlane_b32 s4, v251, 52
	v_readlane_b32 s5, v251, 53
	v_readlane_b32 s8, v251, 56
	v_readlane_b32 s9, v251, 57
	v_readlane_b32 s10, v251, 58
	v_readlane_b32 s11, v251, 59
	v_readlane_b32 s12, v251, 60
	v_readlane_b32 s13, v251, 61
	v_readlane_b32 s14, v251, 62
	v_readlane_b32 s15, v251, 63
	v_readfirstlane_b32 s45, v141
	s_nop 0
	s_add_i32 m0, s45, 0x6000
	s_nop 0
	global_load_lds_dwordx4 v[92:93], off
	s_add_u32 m0, m0, 0x1000
	s_nop 0
	global_load_lds_dwordx4 v[94:95], off
	s_add_u32 m0, m0, 0x1000
	s_nop 0
	global_load_lds_dwordx4 v[132:133], off
	s_add_u32 m0, m0, 0x1000
	s_nop 0
	global_load_lds_dwordx4 v[134:135], off
	s_add_u32 m0, m0, 0x1000
	s_nop 0
	global_load_lds_dwordx4 v[136:137], off
	s_add_u32 m0, m0, 0x1000
	s_nop 0
	global_load_lds_dwordx4 v[138:139], off
	s_waitcnt vmcnt(6)
	s_mov_b32 s47, 0
	s_mov_b32 s48, 0xc000
	s_mov_b64 s[42:43], 64
	s_barrier
